# attention K/V staging: rows of items 1..3 requested at unit start instead of one exposed load latency per item
# speedup vs baseline: 1.0045x; 1.0045x over previous
; #define LAS __attribute__((address_space(3)))
; __device__ __forceinline__ unsigned cvt_pk_bf16(float lo, float hi) { f32x2_t v = {lo, hi}; bf16x2_t b = __builtin_convertvector(v, bf16x2_t); return __builtin_bit_cast(unsigned, b); }
; __device__ __forceinline__ float bflo(unsigned w) { return __uint_as_float(w << 16); }
; __device__ __forceinline__ float bfhi(unsigned w) { return __uint_as_float(w & 0xffff0000u); }
; __device__ __forceinline__ void attn_unit(KArg P, int L, int b, int nb, int kvh, LAS unsigned char* lds) {
;     ...
;     for (int r = 0; r < 4; ++r) { const int item = tid + 512 * r, key = item >> 3, part = item & 7; const int t = nb * 128 - 128 + key;
;         v4u kx = (v4u){0u, 0u, 0u, 0u}, vx = kx;
;         if (t >= 0) { kx = *(const v4u*)(Z + (rowbase + t) * ZW + ZC_AK + kvh * 64 + part * 8); vx = *(const v4u*)(Z + (rowbase + t) * ZW + ZC_AV + kvh * 64 + part * 8); }
;         float kf[8] = {bflo(kx.x), bfhi(kx.x), bflo(kx.y), bfhi(kx.y), bflo(kx.z), bfhi(kx.z), bflo(kx.w), bfhi(kx.w)};
;         float ss = 0.f;
; #pragma unroll
;         for (int e = 0; e < 8; ++e) ss += kf[e] * kf[e];
;         ss += __shfl_xor(ss, 1); ss += __shfl_xor(ss, 2); ss += __shfl_xor(ss, 4);
;         const float rk = rsqrtf(ss * (1.0f / 64.0f) + EPS);
; #pragma unroll
;         for (int e = 0; e < 8; ++e) kf[e] = kf[e] * rk * gk[part * 8 + e];
;         *(LAS v4u*)(lds + AT_K + key * 144 + part * 16) = (v4u){cvt_pk_bf16(kf[0], kf[1]), cvt_pk_bf16(kf[2], kf[3]), cvt_pk_bf16(kf[4], kf[5]), cvt_pk_bf16(kf[6], kf[7])};
;         const unsigned xs[4] = {vx.x, vx.y, vx.z, vx.w};
; #pragma unroll
;         for (int e = 0; e < 8; ++e) { const unsigned wd = xs[e >> 1]; *(LAS bf16*)(lds + AT_VT + (part * 8 + e) * 528 + (key ^ (part << 2)) * 2) = (bf16)((e & 1) ? (wd >> 16) : (wd & 0xffffu)); }
;     }
.LBB0_573:
	v_readlane_b32 s4, v254, 38
	v_mov_b32_e32 v25, v155
	v_readlane_b32 s5, v254, 39
	s_load_dwordx4 s[8:11], s[4:5], 0x68
	s_nop 0
	s_load_dwordx2 s[4:5], s[4:5], 0x78
	s_bfe_u32 s12, s17, 0x50002
	s_lshl_b32 s13, s12, 7
	s_ashr_i32 s0, s17, 7
	v_and_b32_e32 v33, 7, v25
	s_addk_i32 s13, 0xff80
	v_ashrrev_i32_e32 v12, 3, v25
	s_and_b32 s3, s17, 3
	s_waitcnt lgkmcnt(0)
	v_writelane_b32 v255, s4, 2
	s_ashr_i32 s1, s0, 31
	v_lshlrev_b32_e32 v28, 3, v33
	v_add_u32_e32 v0, s13, v12
	v_readfirstlane_b32 s2, v25
	v_writelane_b32 v255, s5, 3
	s_lshl_b64 s[18:19], s[0:1], 12
	s_lshl_b32 s3, s3, 6
	v_readlane_b32 s4, v254, 43
	v_readlane_b32 s5, v254, 44
	v_mov_b32_e32 v100, v0
	v_ashrrev_i32_e32 v101, 31, v0
	v_lshl_add_u64 v[100:101], s[18:19], 0, v[100:101]
	v_mov_b64_e32 v[102:103], s[4:5]
	v_mad_u64_u32 v[102:103], s[6:7], v100, s68, v[102:103]
	v_mad_i32_i24 v103, v101, s68, v103
	s_lshl_b32 s6, s3, 1
	s_mov_b32 s7, 0
	v_lshlrev_b32_e32 v100, 1, v28
	v_mov_b32_e32 v101, 0
	v_lshl_add_u64 v[102:103], v[102:103], 0, s[6:7]
	v_lshl_add_u64 v[102:103], v[102:103], 0, v[100:101]
	v_add_co_u32_e32 v102, vcc, 0xb2000, v102
	s_nop 1
	v_addc_co_u32_e32 v103, vcc, 0, v103, vcc
	global_load_dwordx4 v[104:107], v[102:103], off offset:2048
	global_load_dwordx4 v[108:111], v[102:103], off offset:2560
	v_add_co_u32_e32 v102, vcc, 0xb0000, v102
	s_nop 1
	v_addc_co_u32_e32 v103, vcc, 0, v103, vcc
	global_load_dwordx4 v[112:115], v[102:103], off offset:2048
	global_load_dwordx4 v[116:119], v[102:103], off offset:2560
	v_add_co_u32_e32 v102, vcc, 0xb0000, v102
	s_nop 1
	v_addc_co_u32_e32 v103, vcc, 0, v103, vcc
	global_load_dwordx4 v[120:123], v[102:103], off offset:2048
	global_load_dwordx4 v[124:127], v[102:103], off offset:2560
	v_cmp_lt_i32_e32 vcc, -1, v0
	v_mov_b32_e32 v14, 0
	v_mov_b32_e32 v10, 0
	v_lshlrev_b32_e32 v26, 1, v28
	v_mov_b32_e32 v16, 0
	v_mov_b32_e32 v17, 0
	v_mov_b32_e32 v18, 0
	v_mov_b32_e32 v19, 0
	v_mov_b32_e32 v20, 0
	v_mov_b32_e32 v21, 0
	v_mov_b32_e32 v22, 0
	v_mov_b32_e32 v23, 0
	s_and_saveexec_b64 s[0:1], vcc
	s_cbranch_execz .LBB0_575
	v_readlane_b32 s4, v254, 43
	v_readlane_b32 s5, v254, 44
	v_lshl_add_u64 v[2:3], s[18:19], 0, v[0:1]
	v_mov_b32_e32 v27, v1
	v_mov_b64_e32 v[4:5], s[4:5]
	v_readlane_b32 s4, v254, 34
	v_mad_u64_u32 v[4:5], s[6:7], v2, s68, v[4:5]
	v_readlane_b32 s5, v254, 35
	v_mad_i32_i24 v5, v3, s68, v5
	s_mov_b32 s7, s5
	s_lshl_b32 s6, s3, 1
	v_lshl_add_u64 v[2:3], v[4:5], 0, s[6:7]
	v_lshl_add_u64 v[2:3], v[2:3], 0, v[26:27]
	v_add_co_u32_e32 v2, vcc, 0x2000, v2
	v_writelane_b32 v254, s4, 34
	s_nop 0
	v_addc_co_u32_e32 v3, vcc, 0, v3, vcc
	global_load_dwordx4 v[20:23], v[2:3], off offset:2048
	global_load_dwordx4 v[16:19], v[2:3], off offset:2560
	v_writelane_b32 v254, s5, 35
.LBB0_575:
	s_or_b64 exec, exec, s[0:1]
	s_add_u32 s0, s10, s14
	s_addc_u32 s1, s11, s15
	v_lshlrev_b32_e32 v0, 2, v28
	global_load_dwordx4 v[6:9], v0, s[0:1]
	global_load_dwordx4 v[2:5], v0, s[0:1] offset:16
	v_and_b32_e32 v11, 64, v166
	v_xor_b32_e32 v0, 1, v166
	s_waitcnt vmcnt(3)
	v_lshlrev_b32_e32 v40, 16, v20
	v_and_b32_e32 v41, 0xffff0000, v20
	v_add_u32_e32 v29, 64, v11
	v_lshlrev_b32_e32 v36, 16, v23
	v_and_b32_e32 v37, 0xffff0000, v23
	v_lshlrev_b32_e32 v38, 16, v22
	v_and_b32_e32 v39, 0xffff0000, v22
	v_lshlrev_b32_e32 v22, 16, v21
	v_and_b32_e32 v23, 0xffff0000, v21
	v_pk_mul_f32 v[30:31], v[40:41], v[40:41]
	v_cmp_lt_i32_e32 vcc, v0, v29
	v_pk_mul_f32 v[44:45], v[22:23], v[22:23]
	v_add_f32_e32 v11, v30, v31
	v_cndmask_b32_e32 v0, v166, v0, vcc
	v_lshlrev_b32_e32 v30, 2, v0
	v_add_f32_e32 v0, v44, v11
	v_pk_mul_f32 v[42:43], v[38:39], v[38:39]
	v_add_f32_e32 v0, v45, v0
	v_add_f32_e32 v0, v42, v0
	v_pk_mul_f32 v[20:21], v[36:37], v[36:37]
	v_add_f32_e32 v0, v43, v0
	v_add_f32_e32 v0, v20, v0
	v_add_f32_e32 v0, v21, v0
	ds_bpermute_b32 v11, v30, v0
	v_xor_b32_e32 v13, 2, v166
	v_cmp_lt_i32_e32 vcc, v13, v29
	v_xor_b32_e32 v15, 4, v166
	v_lshl_add_u32 v24, v33, 4, 0
	v_cndmask_b32_e32 v13, v166, v13, vcc
	v_lshlrev_b32_e32 v31, 2, v13
	s_waitcnt lgkmcnt(0)
	v_add_f32_e32 v0, v0, v11
	ds_bpermute_b32 v13, v31, v0
	v_cmp_lt_i32_e32 vcc, v15, v29
	v_lshlrev_b32_e32 v27, 1, v12
	v_or_b32_e32 v35, 2, v28
	v_cndmask_b32_e32 v15, v166, v15, vcc
	v_lshlrev_b32_e32 v32, 2, v15
	s_waitcnt lgkmcnt(0)
	v_add_f32_e32 v0, v0, v13
	ds_bpermute_b32 v15, v32, v0
	v_mad_u64_u32 v[12:13], s[0:1], v12, s86, v[24:25]
	v_xad_u32 v13, v27, v28, 0
	s_movk_i32 s0, 0x1080
	s_waitcnt lgkmcnt(0)
	v_add_f32_e32 v0, v0, v15
	v_mad_u32_u24 v21, v33, s0, v13
	v_fmamk_f32 v0, v0, 0x3c800000, v154
	s_mov_b32 s0, 0x800000
	v_mul_f32_e32 v15, 0x4b800000, v0
	v_cmp_gt_f32_e32 vcc, s0, v0
	v_add_u32_e32 v20, 0x200, v25
	v_ashrrev_i32_e32 v20, 3, v20
	v_cndmask_b32_e32 v0, v0, v15, vcc
	v_rsq_f32_e32 v15, v0
	s_movk_i32 s0, 0x210
	v_mad_u32_u24 v13, v35, s0, v13
	v_add_u32_e32 v0, s13, v20
	v_mul_f32_e32 v27, 0x45800000, v15
	v_cndmask_b32_e32 v34, v15, v27, vcc
	v_pk_mul_f32 v[40:41], v[34:35], v[40:41] op_sel_hi:[0,1]
	v_pk_mul_f32 v[22:23], v[34:35], v[22:23] op_sel_hi:[0,1]
	v_pk_mul_f32 v[38:39], v[34:35], v[38:39] op_sel_hi:[0,1]
	v_pk_mul_f32 v[36:37], v[34:35], v[36:37] op_sel_hi:[0,1]
	v_mov_b32_e32 v11, 0
	v_cmp_lt_i32_e64 s[6:7], -1, v0
	v_mov_b32_e32 v15, 0
	s_waitcnt vmcnt(1)
	v_pk_mul_f32 v[40:41], v[6:7], v[40:41]
	v_pk_mul_f32 v[22:23], v[8:9], v[22:23]
	s_waitcnt vmcnt(0)
	v_pk_mul_f32 v[38:39], v[2:3], v[38:39]
	v_pk_mul_f32 v[42:43], v[4:5], v[36:37]
	v_cvt_pk_bf16_f32 v36, v40, v41
	v_cvt_pk_bf16_f32 v37, v22, v23
	v_cvt_pk_bf16_f32 v38, v38, v39
	v_cvt_pk_bf16_f32 v39, v42, v43
	ds_write_b128 v12, v[36:39]
	ds_write_b16 v21, v16 offset:36864
	ds_write_b16_d16_hi v21, v16 offset:37392
	ds_write_b16 v13, v17 offset:36864
	ds_write_b16_d16_hi v21, v17 offset:38448
	ds_write_b16 v13, v18 offset:37920
	ds_write_b16_d16_hi v21, v18 offset:39504
	ds_write_b16 v13, v19 offset:38976
	ds_write_b16_d16_hi v21, v19 offset:40560
	v_mov_b32_e32 v12, 0
	v_mov_b32_e32 v13, 0
	v_mov_b32_e32 v16, 0
	v_mov_b32_e32 v17, 0
	s_and_saveexec_b64 s[0:1], s[6:7]
	s_cbranch_execz .LBB0_577
	v_readlane_b32 s4, v254, 43
	v_readlane_b32 s5, v254, 44
	v_lshl_add_u64 v[10:11], s[18:19], 0, v[0:1]
	v_mov_b32_e32 v27, v1
	v_mov_b64_e32 v[12:13], s[4:5]
	v_readlane_b32 s4, v254, 34
	v_mad_u64_u32 v[12:13], s[6:7], v10, s68, v[12:13]
	v_readlane_b32 s5, v254, 35
	v_mad_i32_i24 v13, v11, s68, v13
	s_mov_b32 s7, s5
	s_lshl_b32 s6, s3, 1
	v_lshl_add_u64 v[10:11], v[12:13], 0, s[6:7]
	v_lshl_add_u64 v[10:11], v[10:11], 0, v[26:27]
	v_add_co_u32_e32 v10, vcc, 0x2000, v10
	v_writelane_b32 v254, s4, 34
	s_nop 0
	v_addc_co_u32_e32 v11, vcc, 0, v11, vcc
	v_mov_b32_e32 v14, v104
	v_mov_b32_e32 v15, v105
	v_mov_b32_e32 v16, v106
	v_mov_b32_e32 v17, v107
	v_mov_b32_e32 v10, v108
	v_mov_b32_e32 v11, v109
	v_mov_b32_e32 v12, v110
	v_mov_b32_e32 v13, v111
	v_writelane_b32 v254, s5, 35
; #define LAS __attribute__((address_space(3)))
; __device__ __forceinline__ unsigned cvt_pk_bf16(float lo, float hi) { f32x2_t v = {lo, hi}; bf16x2_t b = __builtin_convertvector(v, bf16x2_t); return __builtin_bit_cast(unsigned, b); }
; __device__ __forceinline__ float bflo(unsigned w) { return __uint_as_float(w << 16); }
; __device__ __forceinline__ float bfhi(unsigned w) { return __uint_as_float(w & 0xffff0000u); }
; __device__ __forceinline__ void attn_unit(KArg P, int L, int b, int nb, int kvh, LAS unsigned char* lds) {
;     ...
;     for (int r = 0; r < 4; ++r) { const int item = tid + 512 * r, key = item >> 3, part = item & 7; const int t = nb * 128 - 128 + key;
;         v4u kx = (v4u){0u, 0u, 0u, 0u}, vx = kx;
;         if (t >= 0) { kx = *(const v4u*)(Z + (rowbase + t) * ZW + ZC_AK + kvh * 64 + part * 8); vx = *(const v4u*)(Z + (rowbase + t) * ZW + ZC_AV + kvh * 64 + part * 8); }
;         float kf[8] = {bflo(kx.x), bfhi(kx.x), bflo(kx.y), bfhi(kx.y), bflo(kx.z), bfhi(kx.z), bflo(kx.w), bfhi(kx.w)};
;         float ss = 0.f;
; #pragma unroll
;         for (int e = 0; e < 8; ++e) ss += kf[e] * kf[e];
;         ss += __shfl_xor(ss, 1); ss += __shfl_xor(ss, 2); ss += __shfl_xor(ss, 4);
;         const float rk = rsqrtf(ss * (1.0f / 64.0f) + EPS);
; #pragma unroll
;         for (int e = 0; e < 8; ++e) kf[e] = kf[e] * rk * gk[part * 8 + e];
;         *(LAS v4u*)(lds + AT_K + key * 144 + part * 16) = (v4u){cvt_pk_bf16(kf[0], kf[1]), cvt_pk_bf16(kf[2], kf[3]), cvt_pk_bf16(kf[4], kf[5]), cvt_pk_bf16(kf[6], kf[7])};
;         const unsigned xs[4] = {vx.x, vx.y, vx.z, vx.w};
; #pragma unroll
;         for (int e = 0; e < 8; ++e) { const unsigned wd = xs[e >> 1]; *(LAS bf16*)(lds + AT_VT + (part * 8 + e) * 528 + (key ^ (part << 2)) * 2) = (bf16)((e & 1) ? (wd >> 16) : (wd & 0xffffu)); }
;     }
.LBB0_577:
	s_or_b64 exec, exec, s[0:1]
	s_waitcnt vmcnt(1)
	v_lshlrev_b32_e32 v42, 16, v14
	v_and_b32_e32 v43, 0xffff0000, v14
	v_lshlrev_b32_e32 v38, 16, v15
	v_and_b32_e32 v39, 0xffff0000, v15
	v_pk_mul_f32 v[14:15], v[42:43], v[42:43]
	v_pk_mul_f32 v[40:41], v[38:39], v[38:39]
	v_add_f32_e32 v0, v14, v15
	v_lshlrev_b32_e32 v36, 16, v16
	v_and_b32_e32 v37, 0xffff0000, v16
	v_add_f32_e32 v0, v40, v0
	v_lshlrev_b32_e32 v18, 16, v17
	v_and_b32_e32 v19, 0xffff0000, v17
	v_pk_mul_f32 v[16:17], v[36:37], v[36:37]
	v_add_f32_e32 v0, v41, v0
	v_add_f32_e32 v0, v16, v0
	v_pk_mul_f32 v[22:23], v[18:19], v[18:19]
	v_add_f32_e32 v0, v17, v0
	v_add_f32_e32 v0, v22, v0
	v_add_f32_e32 v0, v23, v0
	ds_bpermute_b32 v14, v30, v0
	s_mov_b32 s0, 0x800000
	v_mul_u32_u24_e32 v34, 0x1080, v33
	v_mul_u32_u24_e32 v33, 0x210, v35
	v_mov_b32_e32 v21, 0
	s_waitcnt lgkmcnt(0)
	v_add_f32_e32 v0, v0, v14
	ds_bpermute_b32 v14, v31, v0
	s_waitcnt lgkmcnt(0)
	v_add_f32_e32 v0, v0, v14
	ds_bpermute_b32 v14, v32, v0
	s_waitcnt lgkmcnt(0)
	v_add_f32_e32 v0, v0, v14
	v_fmamk_f32 v0, v0, 0x3c800000, v154
	v_mul_f32_e32 v14, 0x4b800000, v0
	v_cmp_gt_f32_e32 vcc, s0, v0
	s_nop 1
	v_cndmask_b32_e32 v0, v0, v14, vcc
	v_rsq_f32_e32 v0, v0
	s_nop 0
	v_mul_f32_e32 v14, 0x45800000, v0
	v_cndmask_b32_e32 v0, v0, v14, vcc
	v_pk_mul_f32 v[14:15], v[0:1], v[42:43] op_sel_hi:[0,1]
	v_pk_mul_f32 v[16:17], v[0:1], v[38:39] op_sel_hi:[0,1]
	v_pk_mul_f32 v[22:23], v[0:1], v[36:37] op_sel_hi:[0,1]
	v_pk_mul_f32 v[18:19], v[0:1], v[18:19] op_sel_hi:[0,1]
	v_pk_mul_f32 v[14:15], v[6:7], v[14:15]
	v_pk_mul_f32 v[16:17], v[8:9], v[16:17]
	v_pk_mul_f32 v[22:23], v[2:3], v[22:23]
	v_pk_mul_f32 v[18:19], v[4:5], v[18:19]
	v_lshlrev_b32_e32 v0, 1, v20
	v_cvt_pk_bf16_f32 v14, v14, v15
	v_cvt_pk_bf16_f32 v15, v16, v17
	v_cvt_pk_bf16_f32 v16, v22, v23
	v_cvt_pk_bf16_f32 v17, v18, v19
	v_mad_u64_u32 v[18:19], s[0:1], v20, s86, v[24:25]
	v_xad_u32 v0, v0, v28, 0
	ds_write_b128 v18, v[14:17]
	v_add_u32_e32 v14, v0, v34
	v_add_u32_e32 v0, v0, v33
	s_waitcnt vmcnt(0)
	ds_write_b16 v14, v10 offset:36864
	ds_write_b16_d16_hi v14, v10 offset:37392
	ds_write_b16 v0, v11 offset:36864
	ds_write_b16_d16_hi v14, v11 offset:38448
	ds_write_b16 v0, v12 offset:37920
	ds_write_b16_d16_hi v14, v12 offset:39504
	ds_write_b16 v0, v13 offset:38976
	ds_write_b16_d16_hi v14, v13 offset:40560
	v_add_u32_e32 v0, 0x400, v25
	v_ashrrev_i32_e32 v11, 3, v0
	v_add_u32_e32 v0, s13, v11
	v_cmp_lt_i32_e32 vcc, -1, v0
	v_mov_b32_e32 v14, 0
	v_mov_b32_e32 v10, 0
	v_mov_b32_e32 v16, 0
	v_mov_b32_e32 v17, 0
	v_mov_b32_e32 v18, 0
	v_mov_b32_e32 v19, 0
	v_mov_b32_e32 v20, 0
	v_mov_b32_e32 v22, 0
	v_mov_b32_e32 v23, 0
	s_and_saveexec_b64 s[0:1], vcc
	s_cbranch_execz .LBB0_579
	v_readlane_b32 s4, v254, 43
	v_readlane_b32 s5, v254, 44
	v_lshl_add_u64 v[12:13], s[18:19], 0, v[0:1]
	v_mov_b32_e32 v27, v1
	v_mov_b64_e32 v[16:17], s[4:5]
	v_readlane_b32 s4, v254, 34
	v_mad_u64_u32 v[16:17], s[6:7], v12, s68, v[16:17]
	v_readlane_b32 s5, v254, 35
	v_mad_i32_i24 v17, v13, s68, v17
	s_mov_b32 s7, s5
	s_lshl_b32 s6, s3, 1
	v_lshl_add_u64 v[12:13], v[16:17], 0, s[6:7]
	v_lshl_add_u64 v[12:13], v[12:13], 0, v[26:27]
	v_add_co_u32_e32 v12, vcc, 0x2000, v12
	v_writelane_b32 v254, s4, 34
	s_nop 0
	v_addc_co_u32_e32 v13, vcc, 0, v13, vcc
	v_mov_b32_e32 v20, v112
	v_mov_b32_e32 v21, v113
	v_mov_b32_e32 v22, v114
	v_mov_b32_e32 v23, v115
	v_mov_b32_e32 v16, v116
	v_mov_b32_e32 v17, v117
	v_mov_b32_e32 v18, v118
	v_mov_b32_e32 v19, v119
	v_writelane_b32 v254, s5, 35
.LBB0_579:
	s_or_b64 exec, exec, s[0:1]
	s_waitcnt vmcnt(1)
	v_lshlrev_b32_e32 v44, 16, v20
	v_and_b32_e32 v45, 0xffff0000, v20
	v_lshlrev_b32_e32 v40, 16, v21
	v_and_b32_e32 v41, 0xffff0000, v21
	v_pk_mul_f32 v[20:21], v[44:45], v[44:45]
	v_pk_mul_f32 v[42:43], v[40:41], v[40:41]
	v_add_f32_e32 v0, v20, v21
	v_lshlrev_b32_e32 v38, 16, v22
	v_and_b32_e32 v39, 0xffff0000, v22
	v_add_f32_e32 v0, v42, v0
	v_lshlrev_b32_e32 v12, 16, v23
	v_and_b32_e32 v13, 0xffff0000, v23
	v_pk_mul_f32 v[22:23], v[38:39], v[38:39]
	v_add_f32_e32 v0, v43, v0
	v_add_f32_e32 v0, v22, v0
	v_pk_mul_f32 v[36:37], v[12:13], v[12:13]
	v_add_f32_e32 v0, v23, v0
	v_add_f32_e32 v0, v36, v0
	v_add_f32_e32 v0, v37, v0
	ds_bpermute_b32 v15, v30, v0
	s_mov_b32 s0, 0x800000
	s_waitcnt lgkmcnt(0)
	v_add_f32_e32 v0, v0, v15
	ds_bpermute_b32 v15, v31, v0
	s_waitcnt lgkmcnt(0)
	v_add_f32_e32 v0, v0, v15
	ds_bpermute_b32 v15, v32, v0
	s_waitcnt lgkmcnt(0)
	v_add_f32_e32 v0, v0, v15
	v_fmamk_f32 v0, v0, 0x3c800000, v154
	v_mul_f32_e32 v15, 0x4b800000, v0
	v_cmp_gt_f32_e32 vcc, s0, v0
	s_nop 1
	v_cndmask_b32_e32 v0, v0, v15, vcc
	v_rsq_f32_e32 v0, v0
	s_nop 0
	v_mul_f32_e32 v15, 0x45800000, v0
	v_cndmask_b32_e32 v0, v0, v15, vcc
	v_pk_mul_f32 v[20:21], v[0:1], v[44:45] op_sel_hi:[0,1]
	v_pk_mul_f32 v[22:23], v[0:1], v[40:41] op_sel_hi:[0,1]
	v_pk_mul_f32 v[36:37], v[0:1], v[38:39] op_sel_hi:[0,1]
	v_pk_mul_f32 v[12:13], v[0:1], v[12:13] op_sel_hi:[0,1]
	v_lshlrev_b32_e32 v0, 1, v11
	v_pk_mul_f32 v[20:21], v[6:7], v[20:21]
	v_pk_mul_f32 v[22:23], v[8:9], v[22:23]
	v_pk_mul_f32 v[36:37], v[2:3], v[36:37]
	v_pk_mul_f32 v[12:13], v[4:5], v[12:13]
	v_xad_u32 v0, v0, v28, 0
	v_cvt_pk_bf16_f32 v20, v20, v21
	v_cvt_pk_bf16_f32 v21, v22, v23
	v_cvt_pk_bf16_f32 v22, v36, v37
	v_cvt_pk_bf16_f32 v23, v12, v13
	v_mad_u64_u32 v[12:13], s[0:1], v11, s86, v[24:25]
	v_add_u32_e32 v11, v0, v34
	v_add_u32_e32 v0, v0, v33
	ds_write_b128 v12, v[20:23]
	s_waitcnt vmcnt(0)
	ds_write_b16 v11, v16 offset:36864
	ds_write_b16_d16_hi v11, v16 offset:37392
	ds_write_b16 v0, v17 offset:36864
	ds_write_b16_d16_hi v11, v17 offset:38448
	ds_write_b16 v0, v18 offset:37920
	ds_write_b16_d16_hi v11, v18 offset:39504
	ds_write_b16 v0, v19 offset:38976
	ds_write_b16_d16_hi v11, v19 offset:40560
	v_add_u32_e32 v0, 0x600, v25
	v_ashrrev_i32_e32 v18, 3, v0
	v_add_u32_e32 v0, s13, v18
	v_cmp_lt_i32_e32 vcc, -1, v0
	v_mov_b32_e32 v11, 0
	v_mov_b32_e32 v12, 0
	v_mov_b32_e32 v13, 0
	v_mov_b32_e32 v15, 0
	v_mov_b32_e32 v16, 0
	v_mov_b32_e32 v17, 0
	s_and_saveexec_b64 s[0:1], vcc
	s_cbranch_execz .LBB0_581
	v_readlane_b32 s4, v254, 43
	v_readlane_b32 s5, v254, 44
	v_lshl_add_u64 v[10:11], s[18:19], 0, v[0:1]
	v_mov_b32_e32 v27, v1
	v_mov_b64_e32 v[12:13], s[4:5]
	v_mad_u64_u32 v[12:13], s[6:7], v10, s68, v[12:13]
	v_readlane_b32 s4, v254, 34
	v_mad_i32_i24 v13, v11, s68, v13
	v_readlane_b32 s5, v254, 35
	s_lshl_b32 s4, s3, 1
	s_mov_b32 s3, s5
	v_lshl_add_u64 v[10:11], v[12:13], 0, s[4:5]
	v_lshl_add_u64 v[10:11], v[10:11], 0, v[26:27]
	v_add_co_u32_e32 v10, vcc, 0x2000, v10
	v_writelane_b32 v254, s2, 34
	s_nop 0
	v_addc_co_u32_e32 v11, vcc, 0, v11, vcc
	v_mov_b32_e32 v14, v120
	v_mov_b32_e32 v15, v121
	v_mov_b32_e32 v16, v122
	v_mov_b32_e32 v17, v123
	v_mov_b32_e32 v10, v124
	v_mov_b32_e32 v11, v125
	v_mov_b32_e32 v12, v126
	v_mov_b32_e32 v13, v127
	v_writelane_b32 v254, s3, 35
